# P2 NOMAX loop: pointer SALU + two-chain row-sum (4 fewer v_add_f32 per iteration), P1 LDS tables
# baseline (speedup 1.0000x reference)
.LBB0_1097:
	s_mov_b32 s7, s89
	s_add_u32 s98, s100, s24
	s_mov_b32 s88, s38
	s_addc_u32 s99, s101, s25
	s_mov_b32 s37, s87
	v_add_u32_e32 v198, s36, v233
	ds_read_b64_tr_b16 v[200:201], v198 offset:24576
	ds_read_b64_tr_b16 v[202:203], v198 offset:25088
	v_add_f32_e32 v98, v84, v82
	v_add_f32_e32 v99, v85, v83
	v_add_f32_e32 v98, v86, v98
	v_add_f32_e32 v99, v87, v99
	v_cvt_pk_bf16_f32 v158, v82, v83
	v_cvt_pk_bf16_f32 v159, v84, v85
	s_waitcnt lgkmcnt(9)
	v_mfma_f32_32x32x16_bf16 v[114:129], v[190:193], v[130:133], v[50:65]
	ds_read_b64_tr_b16 v[82:83], v198 offset:28672
	ds_read_b64_tr_b16 v[84:85], v198 offset:29184
	v_add_f32_e32 v98, v88, v98
	v_add_f32_e32 v99, v89, v99
	v_add_f32_e32 v146, v90, v98
	v_add_f32_e32 v147, v91, v99
	s_waitcnt lgkmcnt(10)
	v_mfma_f32_32x32x16_bf16 v[98:113], v[186:189], v[130:133], v[50:65]
	v_cvt_pk_bf16_f32 v160, v86, v87
	v_cvt_pk_bf16_f32 v161, v88, v89
	ds_read_b64_tr_b16 v[86:87], v198 offset:25600
	ds_read_b64_tr_b16 v[88:89], v198 offset:26112
	v_add_f32_e32 v146, v92, v146
	v_add_f32_e32 v147, v93, v147
	v_add_f32_e32 v146, v94, v146
	v_add_f32_e32 v147, v95, v147
	v_cvt_pk_bf16_f32 v154, v90, v91
	v_cvt_pk_bf16_f32 v155, v92, v93
	s_waitcnt lgkmcnt(11)
	v_mfma_f32_32x32x16_bf16 v[114:129], v[182:185], v[134:137], v[114:129]
	ds_read_b64_tr_b16 v[90:91], v198 offset:29696
	ds_read_b64_tr_b16 v[92:93], v198 offset:30208
	s_waitcnt lgkmcnt(12)
	v_mfma_f32_32x32x16_bf16 v[98:113], v[178:181], v[134:137], v[98:113]
	v_add_f32_e32 v146, v96, v146
	v_add_f32_e32 v147, v97, v147
	v_add_f32_e32 v146, v66, v146
	v_add_f32_e32 v147, v67, v147
	v_cvt_pk_bf16_f32 v156, v94, v95
	v_cvt_pk_bf16_f32 v157, v96, v97
	ds_read_b64_tr_b16 v[94:95], v198 offset:26624
	ds_read_b64_tr_b16 v[96:97], v198 offset:27136
	v_add_f32_e32 v146, v68, v146
	v_add_f32_e32 v147, v69, v147
	v_add_f32_e32 v146, v70, v146
	v_add_f32_e32 v147, v71, v147
	v_cvt_pk_bf16_f32 v150, v66, v67
	v_cvt_pk_bf16_f32 v151, v68, v69
	s_waitcnt lgkmcnt(13)
	v_mfma_f32_32x32x16_bf16 v[114:129], v[174:177], v[138:141], v[114:129]
	ds_read_b64_tr_b16 v[66:67], v198 offset:30720
	ds_read_b64_tr_b16 v[68:69], v198 offset:31232
	s_waitcnt lgkmcnt(14)
	v_mfma_f32_32x32x16_bf16 v[98:113], v[170:173], v[138:141], v[98:113]
	v_add_f32_e32 v146, v72, v146
	v_add_f32_e32 v147, v73, v147
	v_add_f32_e32 v146, v74, v146
	v_add_f32_e32 v147, v75, v147
	v_cvt_pk_bf16_f32 v152, v70, v71
	v_cvt_pk_bf16_f32 v153, v72, v73
	ds_read_b64_tr_b16 v[70:71], v198 offset:27648
	ds_read_b64_tr_b16 v[72:73], v198 offset:28160
	v_add_f32_e32 v146, v76, v146
	v_add_f32_e32 v147, v77, v147
	v_add_f32_e32 v170, v78, v146
	v_add_f32_e32 v171, v79, v147
	v_cvt_pk_bf16_f32 v146, v74, v75
	v_cvt_pk_bf16_f32 v147, v76, v77
	s_waitcnt lgkmcnt(14)
	v_mfma_f32_32x32x16_bf16 v[114:129], v[166:169], v[142:145], v[114:129]
	ds_read_b64_tr_b16 v[74:75], v198 offset:31744
	ds_read_b64_tr_b16 v[76:77], v198 offset:32256
	v_mfma_f32_32x32x16_bf16 v[98:113], v[162:165], v[142:145], v[98:113]
	v_add_f32_e32 v148, v80, v170
	v_add_f32_e32 v149, v81, v171
	v_add_f32_e32 v198, v148, v149
	v_cvt_pk_bf16_f32 v148, v78, v79
	v_cvt_pk_bf16_f32 v149, v80, v81
	s_add_i32 s0, s87, s84
	s_mov_b32 s1, m0
	s_mov_b32 m0, s0
	s_nop 0
	global_load_lds_dwordx4 v196, s[98:99]
	s_mov_b32 m0, s1
	s_add_i32 s0, s89, s8
	s_mov_b32 s1, m0
	s_mov_b32 m0, s0
	s_nop 0
	global_load_lds_dwordx4 v194, s[98:99]
	s_mov_b32 m0, s1
	s_waitcnt lgkmcnt(14)
	v_mfma_f32_32x32x16_bf16 v[18:33], v[158:161], v[200:203], v[18:33]
	v_exp_f32_e32 v114, v114
	v_exp_f32_e32 v115, v115
	v_exp_f32_e32 v116, v116
	v_exp_f32_e32 v117, v117
	s_waitcnt lgkmcnt(12)
	v_mfma_f32_32x32x16_bf16 v[34:49], v[158:161], v[82:85], v[34:49]
	v_exp_f32_e32 v118, v118
	v_exp_f32_e32 v119, v119
	v_exp_f32_e32 v120, v120
	v_exp_f32_e32 v121, v121
	v_add_u32_e32 v82, s7, v232
	ds_read_b128 v[78:81], v82
	ds_read_b128 v[162:165], v82 offset:512
	s_waitcnt lgkmcnt(12)
	v_mfma_f32_32x32x16_bf16 v[18:33], v[154:157], v[86:89], v[18:33]
	v_exp_f32_e32 v122, v122
	v_exp_f32_e32 v123, v123
	v_exp_f32_e32 v124, v124
	v_exp_f32_e32 v125, v125
	ds_read_b128 v[166:169], v82 offset:2048
	ds_read_b128 v[170:173], v82 offset:2560
	s_waitcnt lgkmcnt(12)
	v_mfma_f32_32x32x16_bf16 v[34:49], v[154:157], v[90:93], v[34:49]
	v_exp_f32_e32 v126, v126
	v_exp_f32_e32 v127, v127
	v_exp_f32_e32 v128, v128
	v_exp_f32_e32 v129, v129
	ds_read_b128 v[174:177], v82 offset:4096
	ds_read_b128 v[178:181], v82 offset:4608
	s_waitcnt lgkmcnt(12)
	v_mfma_f32_32x32x16_bf16 v[18:33], v[150:153], v[94:97], v[18:33]
	v_exp_f32_e32 v98, v98
	v_exp_f32_e32 v99, v99
	v_exp_f32_e32 v100, v100
	v_exp_f32_e32 v101, v101
	ds_read_b128 v[182:185], v82 offset:6144
	ds_read_b128 v[186:189], v82 offset:6656
	s_waitcnt lgkmcnt(12)
	v_mfma_f32_32x32x16_bf16 v[34:49], v[150:153], v[66:69], v[34:49]
	v_exp_f32_e32 v102, v102
	v_exp_f32_e32 v103, v103
	v_exp_f32_e32 v104, v104
	v_exp_f32_e32 v105, v105
	s_waitcnt lgkmcnt(10)
	v_mfma_f32_32x32x16_bf16 v[18:33], v[146:149], v[70:73], v[18:33]
	v_exp_f32_e32 v106, v106
	v_exp_f32_e32 v107, v107
	v_exp_f32_e32 v108, v108
	v_exp_f32_e32 v109, v109
	s_waitcnt lgkmcnt(8)
	v_mfma_f32_32x32x16_bf16 v[34:49], v[146:149], v[74:77], v[34:49]
	v_exp_f32_e32 v110, v110
	v_exp_f32_e32 v111, v111
	v_exp_f32_e32 v112, v112
	v_exp_f32_e32 v113, v113
	s_waitcnt vmcnt(2) lgkmcnt(0)
	s_barrier
; #define WAIT_BAR(N) asm volatile("s_waitcnt vmcnt(" #N ") lgkmcnt(0)\n\ts_barrier":::"memory")
;   #define RESC() do{ if(resc){ asm volatile("s_waitcnt lgkmcnt(0)":::"memory"); \
;       _Pragma("unroll") for(int d_=0;d_<2;++d_) _Pragma("unroll") for(int r=0;r<16;++r)o[d_][r]*=wsf[crow(r,hi)]; } }while(0)
;   #define ROT() do{sl_prev=sl_cur;sl_cur=sl_next;sl_next=(sl_next==(NSLOT-1)*SLOTB)?0:sl_next+SLOTB;}while(0)
; template<int THRL,bool NOMAX> __device__ __forceinline__ void attn_unit(long rowbase,int NT,int h,int qb,const bf16*Q,const bf16*__restrict__ Kh,const bf16*__restrict__ Vh,bf16*O,char*shm,
;     bool first,bool has_next,long n_rowbase,int n_h,int n_qb,const bf16*__restrict__ n_Kh,bf16x8 (&qr)[4]){
;     ...
;   int t=1;
;     ...
;   for(;t+5<NT;t+=2){
;     STEP(pB0,pB1,pA0,pA1,t,true,true,true);     WAIT_BAR(2); RESC(); ROT();
;     STEP(pA0,pA1,pB0,pB1,t+1,true,true,true);   WAIT_BAR(2); RESC(); ROT();
	s_add_i32 s0, s89, 0x2000
	s_cmpk_lg_i32 s89, 0x4000
	s_cselect_b32 s87, s0, 0
	v_add_u32_e32 v199, s37, v233
	ds_read_b64_tr_b16 v[190:191], v199 offset:24576
	ds_read_b64_tr_b16 v[192:193], v199 offset:25088
	s_waitcnt lgkmcnt(9)
	v_mfma_f32_32x32x16_bf16 v[82:97], v[78:81], v[130:133], v[50:65]
	v_add_f32_e32 v66, v116, v114
	v_add_f32_e32 v67, v117, v115
	v_add_f32_e32 v66, v118, v66
	v_add_f32_e32 v67, v119, v67
	v_cvt_pk_bf16_f32 v158, v114, v115
	v_cvt_pk_bf16_f32 v159, v116, v117
	ds_read_b64_tr_b16 v[114:115], v199 offset:28672
	ds_read_b64_tr_b16 v[116:117], v199 offset:29184
	v_add_f32_e32 v66, v120, v66
	v_add_f32_e32 v67, v121, v67
	v_add_f32_e32 v146, v122, v66
	v_add_f32_e32 v147, v123, v67
	s_waitcnt lgkmcnt(10)
	v_mfma_f32_32x32x16_bf16 v[66:81], v[162:165], v[130:133], v[50:65]
	v_cvt_pk_bf16_f32 v160, v118, v119
	v_cvt_pk_bf16_f32 v161, v120, v121
	ds_read_b64_tr_b16 v[118:119], v199 offset:25600
	ds_read_b64_tr_b16 v[120:121], v199 offset:26112
	s_waitcnt lgkmcnt(11)
	v_mfma_f32_32x32x16_bf16 v[82:97], v[166:169], v[134:137], v[82:97]
	v_add_f32_e32 v146, v124, v146
	v_add_f32_e32 v147, v125, v147
	v_add_f32_e32 v146, v126, v146
	v_add_f32_e32 v147, v127, v147
	v_cvt_pk_bf16_f32 v154, v122, v123
	v_cvt_pk_bf16_f32 v155, v124, v125
	ds_read_b64_tr_b16 v[122:123], v199 offset:29696
	ds_read_b64_tr_b16 v[124:125], v199 offset:30208
	s_waitcnt lgkmcnt(12)
	v_mfma_f32_32x32x16_bf16 v[66:81], v[170:173], v[134:137], v[66:81]
	v_add_f32_e32 v146, v128, v146
	v_add_f32_e32 v147, v129, v147
	v_add_f32_e32 v146, v98, v146
	v_add_f32_e32 v147, v99, v147
	v_cvt_pk_bf16_f32 v156, v126, v127
	v_cvt_pk_bf16_f32 v157, v128, v129
	ds_read_b64_tr_b16 v[126:127], v199 offset:26624
	ds_read_b64_tr_b16 v[128:129], v199 offset:27136
	s_waitcnt lgkmcnt(13)
	v_mfma_f32_32x32x16_bf16 v[82:97], v[174:177], v[138:141], v[82:97]
	v_add_f32_e32 v146, v100, v146
	v_add_f32_e32 v147, v101, v147
	v_add_f32_e32 v146, v102, v146
	v_add_f32_e32 v147, v103, v147
	v_cvt_pk_bf16_f32 v150, v98, v99
	v_cvt_pk_bf16_f32 v151, v100, v101
	ds_read_b64_tr_b16 v[98:99], v199 offset:30720
	ds_read_b64_tr_b16 v[100:101], v199 offset:31232
	s_waitcnt lgkmcnt(14)
	v_mfma_f32_32x32x16_bf16 v[66:81], v[178:181], v[138:141], v[66:81]
	v_add_f32_e32 v146, v104, v146
	v_add_f32_e32 v147, v105, v147
	v_add_f32_e32 v146, v106, v146
	v_add_f32_e32 v147, v107, v147
	v_cvt_pk_bf16_f32 v152, v102, v103
	v_cvt_pk_bf16_f32 v153, v104, v105
	ds_read_b64_tr_b16 v[102:103], v199 offset:27648
	ds_read_b64_tr_b16 v[104:105], v199 offset:28160
	s_waitcnt lgkmcnt(14)
	v_mfma_f32_32x32x16_bf16 v[82:97], v[182:185], v[142:145], v[82:97]
	v_add_f32_e32 v146, v108, v146
	v_add_f32_e32 v147, v109, v147
	v_add_f32_e32 v162, v110, v146
	v_add_f32_e32 v163, v111, v147
	v_cvt_pk_bf16_f32 v146, v106, v107
	v_cvt_pk_bf16_f32 v147, v108, v109
	ds_read_b64_tr_b16 v[106:107], v199 offset:31744
	ds_read_b64_tr_b16 v[108:109], v199 offset:32256
	v_mfma_f32_32x32x16_bf16 v[66:81], v[186:189], v[142:145], v[66:81]
	v_add_f32_e32 v148, v112, v162
	v_add_f32_e32 v149, v113, v163
	v_add_f32_e32 v199, v148, v149
	v_cvt_pk_bf16_f32 v148, v110, v111
	v_cvt_pk_bf16_f32 v149, v112, v113
	s_add_i32 s0, s89, s84
	s_mov_b32 s1, m0
	s_mov_b32 m0, s0
	s_nop 0
	global_load_lds_dwordx4 v196, s[100:101]
	s_mov_b32 m0, s1
	s_add_i32 s0, s87, s8
	s_mov_b32 s1, m0
	s_mov_b32 m0, s0
	s_nop 0
	global_load_lds_dwordx4 v194, s[100:101]
	s_mov_b32 m0, s1
	s_waitcnt lgkmcnt(14)
	v_mfma_f32_32x32x16_bf16 v[18:33], v[158:161], v[190:193], v[18:33]
	v_exp_f32_e32 v82, v82
	v_exp_f32_e32 v83, v83
	v_exp_f32_e32 v84, v84
	v_exp_f32_e32 v85, v85
	s_waitcnt lgkmcnt(12)
	v_mfma_f32_32x32x16_bf16 v[34:49], v[158:161], v[114:117], v[34:49]
	v_exp_f32_e32 v86, v86
	v_exp_f32_e32 v87, v87
	v_exp_f32_e32 v88, v88
	v_exp_f32_e32 v89, v89
	v_add_u32_e32 v110, s87, v232
	ds_read_b128 v[190:193], v110
	ds_read_b128 v[186:189], v110 offset:512
	s_waitcnt lgkmcnt(12)
	v_mfma_f32_32x32x16_bf16 v[18:33], v[154:157], v[118:121], v[18:33]
	v_exp_f32_e32 v90, v90
	v_exp_f32_e32 v91, v91
	v_exp_f32_e32 v92, v92
	v_exp_f32_e32 v93, v93
	ds_read_b128 v[182:185], v110 offset:2048
	ds_read_b128 v[178:181], v110 offset:2560
	s_waitcnt lgkmcnt(12)
	v_mfma_f32_32x32x16_bf16 v[34:49], v[154:157], v[122:125], v[34:49]
	v_exp_f32_e32 v94, v94
	v_exp_f32_e32 v95, v95
	v_exp_f32_e32 v96, v96
	v_exp_f32_e32 v97, v97
	ds_read_b128 v[174:177], v110 offset:4096
	ds_read_b128 v[170:173], v110 offset:4608
	s_waitcnt lgkmcnt(12)
	v_mfma_f32_32x32x16_bf16 v[18:33], v[150:153], v[126:129], v[18:33]
	v_exp_f32_e32 v66, v66
	v_exp_f32_e32 v67, v67
	v_exp_f32_e32 v68, v68
	v_exp_f32_e32 v69, v69
	ds_read_b128 v[166:169], v110 offset:6144
	ds_read_b128 v[162:165], v110 offset:6656
	s_waitcnt lgkmcnt(12)
	v_mfma_f32_32x32x16_bf16 v[34:49], v[150:153], v[98:101], v[34:49]
	v_exp_f32_e32 v70, v70
	v_exp_f32_e32 v71, v71
	v_exp_f32_e32 v72, v72
	v_exp_f32_e32 v73, v73
	s_waitcnt lgkmcnt(10)
	v_mfma_f32_32x32x16_bf16 v[18:33], v[146:149], v[102:105], v[18:33]
	v_exp_f32_e32 v74, v74
	v_exp_f32_e32 v75, v75
	v_exp_f32_e32 v76, v76
	v_exp_f32_e32 v77, v77
	s_waitcnt lgkmcnt(8)
	v_mfma_f32_32x32x16_bf16 v[34:49], v[146:149], v[106:109], v[34:49]
	v_exp_f32_e32 v78, v78
	v_exp_f32_e32 v79, v79
	v_exp_f32_e32 v80, v80
	v_exp_f32_e32 v81, v81
	s_add_i32 s0, s87, 0x2000
	s_waitcnt vmcnt(2) lgkmcnt(0)
	s_barrier
	s_cmpk_lg_i32 s87, 0x4000
	v_add_f32_e32 v102, v206, v198
	s_mov_b32 s36, s89
	s_cselect_b32 s89, s0, 0
	s_add_i32 s6, s6, 2
	s_add_i32 s38, s38, 2
	s_add_u32 s100, s100, s14
	s_addc_u32 s101, s101, s15
	s_cmp_ge_u32 s6, s82
	v_add_f32_e32 v206, v102, v199
	s_cbranch_scc0 .LBB0_1097
	s_sub_u32 s98, s100, s62
	s_subb_u32 s99, s101, s63
	s_sub_u32 s98, s98, s14
	s_subb_u32 s99, s99, s15
	v_lshl_add_u64 v[226:227], v[226:227], 0, s[98:99]
	v_lshl_add_u64 v[228:229], v[228:229], 0, s[98:99]
	s_add_i32 s0, s6, -4
	s_cmp_ge_u32 s0, s82
	s_cbranch_scc1 .LBB0_1132
	s_add_i32 s90, s6, -5
